# v16: v12 + accumulator zeroing with 64 v_mov_b64 instead of 128 v_mov_b32 per unit
# baseline (speedup 1.0000x reference)
; template <class Epi>
; __device__ __forceinline__ void gemm_phase(LAS unsigned char* lds, const Gemm g, const StaticOrder& S, const Epi& E) {
;     ...
;         const bool has_next = S.next(ui + 1, nxt);
;         const char* nA = has_next ? (const char*)g.A + (size_t)nxt.pm * tstepA + (size_t)nxt.pn * ksb : cA; const char* nB = has_next ? (const char*)g.Bt + (size_t)nxt.pn * bstep : cB;
;     ...
; #pragma unroll
;         for (int a = 0; a < 2; ++a)
; #pragma unroll
;             for (int b = 0; b < 2; ++b)
; #pragma unroll
;                 for (int m = 0; m < 4; ++m)
; #pragma unroll
;                     for (int n = 0; n < 2; ++n) acc[a][b][m][n] = (f32x4){0.f, 0.f, 0.f, 0.f};
;         cur = nxt; cA = nA; cB = nB; ++ui;
.LBB0_52:
	s_ashr_i32 s29, s28, 31
	s_lshl_b64 s[16:17], s[28:29], 19
	s_add_u32 s74, s44, s16
	s_addc_u32 s75, s45, s17
	s_and_b64 s[16:17], s[12:13], exec
	s_cselect_b32 s18, s75, s15
	s_cselect_b32 s19, s74, s14
	s_ashr_i32 s63, s62, 31
	s_lshl_b64 s[16:17], s[62:63], 19
	s_add_u32 s30, s46, s16
	s_addc_u32 s31, s47, s17
	s_and_b64 s[16:17], s[12:13], exec
	s_cselect_b32 s29, s31, s1
	s_cselect_b32 s36, s30, s0
	s_add_u32 s37, s0, 0x100
	s_addc_u32 s63, s1, 0
	s_add_u32 s0, s14, 0x40080
	s_addc_u32 s1, s15, 0
	s_mov_b32 s68, -2
	s_waitcnt vmcnt(0)
	v_mov_b64_e32 v[0:1], 0
	v_mov_b64_e32 v[2:3], 0
	v_mov_b64_e32 v[4:5], 0
	v_mov_b64_e32 v[6:7], 0
	v_mov_b64_e32 v[8:9], 0
	v_mov_b64_e32 v[10:11], 0
	v_mov_b64_e32 v[12:13], 0
	v_mov_b64_e32 v[14:15], 0
	v_mov_b64_e32 v[18:19], 0
	v_mov_b64_e32 v[20:21], 0
	v_mov_b64_e32 v[22:23], 0
	v_mov_b64_e32 v[24:25], 0
	v_mov_b64_e32 v[26:27], 0
	v_mov_b64_e32 v[28:29], 0
	v_mov_b64_e32 v[30:31], 0
	v_mov_b64_e32 v[32:33], 0
	v_mov_b64_e32 v[34:35], 0
	v_mov_b64_e32 v[36:37], 0
	v_mov_b64_e32 v[38:39], 0
	v_mov_b64_e32 v[40:41], 0
	v_mov_b64_e32 v[42:43], 0
	v_mov_b64_e32 v[44:45], 0
	v_mov_b64_e32 v[46:47], 0
	v_mov_b64_e32 v[48:49], 0
	v_mov_b64_e32 v[50:51], 0
	v_mov_b64_e32 v[52:53], 0
	v_mov_b64_e32 v[54:55], 0
	v_mov_b64_e32 v[56:57], 0
	v_mov_b64_e32 v[58:59], 0
	v_mov_b64_e32 v[60:61], 0
	v_mov_b64_e32 v[62:63], 0
	v_mov_b64_e32 v[64:65], 0
	v_mov_b64_e32 v[66:67], 0
	v_mov_b64_e32 v[68:69], 0
	v_mov_b64_e32 v[70:71], 0
	v_mov_b64_e32 v[72:73], 0
	v_mov_b64_e32 v[74:75], 0
	v_mov_b64_e32 v[76:77], 0
	v_mov_b64_e32 v[78:79], 0
	v_mov_b64_e32 v[80:81], 0
	v_mov_b64_e32 v[82:83], 0
	v_mov_b64_e32 v[84:85], 0
	v_mov_b64_e32 v[86:87], 0
	v_mov_b64_e32 v[88:89], 0
	v_mov_b64_e32 v[90:91], 0
	v_mov_b64_e32 v[92:93], 0
	v_mov_b64_e32 v[94:95], 0
	v_mov_b64_e32 v[96:97], 0
	v_mov_b64_e32 v[98:99], 0
	v_mov_b64_e32 v[100:101], 0
	v_mov_b64_e32 v[102:103], 0
	v_mov_b64_e32 v[104:105], 0
	v_mov_b64_e32 v[106:107], 0
	v_mov_b64_e32 v[108:109], 0
	v_mov_b64_e32 v[110:111], 0
	v_mov_b64_e32 v[112:113], 0
	v_mov_b64_e32 v[114:115], 0
	v_mov_b64_e32 v[116:117], 0
	v_mov_b64_e32 v[118:119], 0
	v_mov_b64_e32 v[120:121], 0
	v_mov_b64_e32 v[122:123], 0
	v_mov_b64_e32 v[124:125], 0
	v_mov_b64_e32 v[126:127], 0
	v_mov_b64_e32 v[128:129], 0

; template <class Epi>
; __device__ __forceinline__ void gemm_phase(LAS unsigned char* lds, const Gemm g, const StaticOrder& S, const Epi& E) {
;     ...
;         const bool has_next = S.next(ui + 1, nxt);
;         const char* nA = has_next ? (const char*)g.A + (size_t)nxt.pm * tstepA + (size_t)nxt.pn * ksb : cA; const char* nB = has_next ? (const char*)g.Bt + (size_t)nxt.pn * bstep : cB;
;     ...
; #pragma unroll
;         for (int a = 0; a < 2; ++a)
; #pragma unroll
;             for (int b = 0; b < 2; ++b)
; #pragma unroll
;                 for (int m = 0; m < 4; ++m)
; #pragma unroll
;                     for (int n = 0; n < 2; ++n) acc[a][b][m][n] = (f32x4){0.f, 0.f, 0.f, 0.f};
;         cur = nxt; cA = nA; cB = nB; ++ui;
.LBB0_426:
	s_ashr_i32 s21, s20, 31
	s_lshl_b64 s[22:23], s[20:21], 19
	s_add_u32 s2, s34, s22
	s_addc_u32 s21, s35, s23
	s_ashr_i32 s19, s18, 31
	s_lshl_b64 s[24:25], s[18:19], 10
	s_add_u32 s22, s2, s24
	s_addc_u32 s23, s21, s25
	s_and_b64 s[30:31], s[12:13], exec
	s_cselect_b32 s19, s23, s29
	s_cselect_b32 s21, s22, s28
	s_add_u32 s24, s36, s24
	s_addc_u32 s25, s37, s25
	s_and_b64 s[30:31], s[12:13], exec
	s_mov_b64 s[54:55], s[46:47]
	s_cselect_b32 s46, s25, s1
	s_cselect_b32 s47, s24, s0
	s_add_u32 s48, s0, 0x100
	s_addc_u32 s49, s1, 0
	s_add_u32 s0, s28, 0x40080
	s_addc_u32 s1, s29, 0
	s_mov_b32 s50, -2
	v_mov_b64_e32 v[0:1], 0
	v_mov_b64_e32 v[2:3], 0
	v_mov_b64_e32 v[4:5], 0
	v_mov_b64_e32 v[6:7], 0
	v_mov_b64_e32 v[8:9], 0
	v_mov_b64_e32 v[10:11], 0
	v_mov_b64_e32 v[12:13], 0
	v_mov_b64_e32 v[14:15], 0
	v_mov_b64_e32 v[18:19], 0
	v_mov_b64_e32 v[20:21], 0
	v_mov_b64_e32 v[22:23], 0
	v_mov_b64_e32 v[24:25], 0
	v_mov_b64_e32 v[26:27], 0
	v_mov_b64_e32 v[28:29], 0
	v_mov_b64_e32 v[30:31], 0
	v_mov_b64_e32 v[32:33], 0
	v_mov_b64_e32 v[34:35], 0
	v_mov_b64_e32 v[36:37], 0
	v_mov_b64_e32 v[38:39], 0
	v_mov_b64_e32 v[40:41], 0
	v_mov_b64_e32 v[42:43], 0
	v_mov_b64_e32 v[44:45], 0
	v_mov_b64_e32 v[46:47], 0
	v_mov_b64_e32 v[48:49], 0
	v_mov_b64_e32 v[50:51], 0
	v_mov_b64_e32 v[52:53], 0
	v_mov_b64_e32 v[54:55], 0
	v_mov_b64_e32 v[56:57], 0
	v_mov_b64_e32 v[58:59], 0
	v_mov_b64_e32 v[60:61], 0
	v_mov_b64_e32 v[62:63], 0
	v_mov_b64_e32 v[64:65], 0
	v_mov_b64_e32 v[66:67], 0
	v_mov_b64_e32 v[68:69], 0
	v_mov_b64_e32 v[70:71], 0
	v_mov_b64_e32 v[72:73], 0
	v_mov_b64_e32 v[74:75], 0
	v_mov_b64_e32 v[76:77], 0
	v_mov_b64_e32 v[78:79], 0
	v_mov_b64_e32 v[80:81], 0
	v_mov_b64_e32 v[82:83], 0
	v_mov_b64_e32 v[84:85], 0
	v_mov_b64_e32 v[86:87], 0
	v_mov_b64_e32 v[88:89], 0
	v_mov_b64_e32 v[90:91], 0
	v_mov_b64_e32 v[92:93], 0
	v_mov_b64_e32 v[94:95], 0
	v_mov_b64_e32 v[96:97], 0
	v_mov_b64_e32 v[98:99], 0
	v_mov_b64_e32 v[100:101], 0
	v_mov_b64_e32 v[102:103], 0
	v_mov_b64_e32 v[104:105], 0
	v_mov_b64_e32 v[106:107], 0
	v_mov_b64_e32 v[108:109], 0
	v_mov_b64_e32 v[110:111], 0
	v_mov_b64_e32 v[112:113], 0
	v_mov_b64_e32 v[114:115], 0
	v_mov_b64_e32 v[116:117], 0
	v_mov_b64_e32 v[118:119], 0
	v_mov_b64_e32 v[120:121], 0
	v_mov_b64_e32 v[122:123], 0
	v_mov_b64_e32 v[124:125], 0
	v_mov_b64_e32 v[126:127], 0
	v_mov_b64_e32 v[128:129], 0

; template <class Epi>
; __device__ __forceinline__ void gemm_phase(LAS unsigned char* lds, const Gemm g, const StaticOrder& S, const Epi& E) {
;     ...
;         const bool has_next = S.next(ui + 1, nxt);
;         const char* nA = has_next ? (const char*)g.A + (size_t)nxt.pm * tstepA + (size_t)nxt.pn * ksb : cA; const char* nB = has_next ? (const char*)g.Bt + (size_t)nxt.pn * bstep : cB;
;     ...
; #pragma unroll
;         for (int a = 0; a < 2; ++a)
; #pragma unroll
;             for (int b = 0; b < 2; ++b)
; #pragma unroll
;                 for (int m = 0; m < 4; ++m)
; #pragma unroll
;                     for (int n = 0; n < 2; ++n) acc[a][b][m][n] = (f32x4){0.f, 0.f, 0.f, 0.f};
;         cur = nxt; cA = nA; cB = nB; ++ui;
.LBB0_449:
	s_ashr_i32 s43, s42, 31
	s_lshl_b64 s[20:21], s[42:43], s44
	s_add_u32 s2, s45, s20
	s_addc_u32 s22, s46, s21
	s_and_b64 s[20:21], s[16:17], exec
	s_cselect_b32 s63, s22, s19
	s_cselect_b32 s62, s2, s18
	s_ashr_i32 s41, s40, 31
	s_lshl_b64 s[20:21], s[40:41], s44
	s_add_u32 s2, s47, s20
	s_addc_u32 s22, s48, s21
	s_and_b64 s[20:21], s[16:17], exec
	s_cselect_b32 s65, s22, s1
	s_cselect_b32 s64, s2, s0
	s_add_u32 s20, s0, 0x100
	s_addc_u32 s21, s1, 0
	s_add_u32 s0, s18, 0x80
	s_addc_u32 s1, s19, 0
	s_mov_b32 s18, 0
	s_waitcnt vmcnt(0)
	s_waitcnt vmcnt(0)
	v_mov_b64_e32 v[0:1], 0
	v_mov_b64_e32 v[2:3], 0
	v_mov_b64_e32 v[4:5], 0
	v_mov_b64_e32 v[6:7], 0
	v_mov_b64_e32 v[8:9], 0
	v_mov_b64_e32 v[10:11], 0
	v_mov_b64_e32 v[12:13], 0
	v_mov_b64_e32 v[14:15], 0
	v_mov_b64_e32 v[18:19], 0
	v_mov_b64_e32 v[20:21], 0
	v_mov_b64_e32 v[22:23], 0
	v_mov_b64_e32 v[24:25], 0
	v_mov_b64_e32 v[26:27], 0
	v_mov_b64_e32 v[28:29], 0
	v_mov_b64_e32 v[30:31], 0
	v_mov_b64_e32 v[32:33], 0
	v_mov_b64_e32 v[34:35], 0
	v_mov_b64_e32 v[36:37], 0
	v_mov_b64_e32 v[42:43], 0
	v_mov_b64_e32 v[44:45], 0
	v_mov_b64_e32 v[50:51], 0
	v_mov_b64_e32 v[52:53], 0
	v_mov_b64_e32 v[62:63], 0
	v_mov_b64_e32 v[64:65], 0
	v_mov_b64_e32 v[66:67], 0
	v_mov_b64_e32 v[68:69], 0
	v_mov_b64_e32 v[70:71], 0
	v_mov_b64_e32 v[72:73], 0
	v_mov_b64_e32 v[74:75], 0
	v_mov_b64_e32 v[76:77], 0
	v_mov_b64_e32 v[78:79], 0
	v_mov_b64_e32 v[80:81], 0
	v_mov_b64_e32 v[82:83], 0
	v_mov_b64_e32 v[84:85], 0
	v_mov_b64_e32 v[86:87], 0
	v_mov_b64_e32 v[88:89], 0
	v_mov_b64_e32 v[90:91], 0
	v_mov_b64_e32 v[92:93], 0
	v_mov_b64_e32 v[94:95], 0
	v_mov_b64_e32 v[96:97], 0
	v_mov_b64_e32 v[98:99], 0
	v_mov_b64_e32 v[100:101], 0
	v_mov_b64_e32 v[102:103], 0
	v_mov_b64_e32 v[104:105], 0
	v_mov_b64_e32 v[106:107], 0
	v_mov_b64_e32 v[108:109], 0
	v_mov_b64_e32 v[110:111], 0
	v_mov_b64_e32 v[112:113], 0
	v_mov_b64_e32 v[114:115], 0
	v_mov_b64_e32 v[116:117], 0
	v_mov_b64_e32 v[118:119], 0
	v_mov_b64_e32 v[120:121], 0
	v_mov_b64_e32 v[122:123], 0
	v_mov_b64_e32 v[124:125], 0
	v_mov_b64_e32 v[126:127], 0
	v_mov_b64_e32 v[128:129], 0
	v_mov_b64_e32 v[130:131], 0
	v_mov_b64_e32 v[132:133], 0
	v_mov_b64_e32 v[134:135], 0
	v_mov_b64_e32 v[136:137], 0
	v_mov_b64_e32 v[138:139], 0
	v_mov_b64_e32 v[140:141], 0
	v_mov_b64_e32 v[142:143], 0
	v_mov_b64_e32 v[144:145], 0

; template <class Epi>
; __device__ __forceinline__ void gemm_phase(LAS unsigned char* lds, const Gemm g, const StaticOrder& S, const Epi& E) {
;     ...
; #pragma unroll
;         for (int a = 0; a < 2; ++a)
; #pragma unroll
;             for (int b = 0; b < 2; ++b)
; #pragma unroll
;                 for (int m = 0; m < 4; ++m)
; #pragma unroll
;                     for (int n = 0; n < 2; ++n) acc[a][b][m][n] = (f32x4){0.f, 0.f, 0.f, 0.f};
;         cur = nxt; cA = nA; cB = nB; ++ui;
.LBB0_650:
	s_add_u32 s35, s38, 0x100
	s_addc_u32 s37, s39, 0
	s_add_u32 s38, s40, s100
	s_addc_u32 s39, s41, 0
	s_mov_b32 s40, 0
	v_mov_b64_e32 v[0:1], 0
	v_mov_b64_e32 v[2:3], 0
	v_mov_b64_e32 v[4:5], 0
	v_mov_b64_e32 v[6:7], 0
	v_mov_b64_e32 v[8:9], 0
	v_mov_b64_e32 v[10:11], 0
	v_mov_b64_e32 v[12:13], 0
	v_mov_b64_e32 v[14:15], 0
	v_mov_b64_e32 v[18:19], 0
	v_mov_b64_e32 v[20:21], 0
	v_mov_b64_e32 v[22:23], 0
	v_mov_b64_e32 v[24:25], 0
	v_mov_b64_e32 v[26:27], 0
	v_mov_b64_e32 v[28:29], 0
	v_mov_b64_e32 v[30:31], 0
	v_mov_b64_e32 v[32:33], 0
	v_mov_b64_e32 v[34:35], 0
	v_mov_b64_e32 v[36:37], 0
	v_mov_b64_e32 v[38:39], 0
	v_mov_b64_e32 v[40:41], 0
	v_mov_b64_e32 v[42:43], 0
	v_mov_b64_e32 v[44:45], 0
	v_mov_b64_e32 v[46:47], 0
	v_mov_b64_e32 v[48:49], 0
	v_mov_b64_e32 v[50:51], 0
	v_mov_b64_e32 v[52:53], 0
	v_mov_b64_e32 v[54:55], 0
	v_mov_b64_e32 v[56:57], 0
	v_mov_b64_e32 v[58:59], 0
	v_mov_b64_e32 v[60:61], 0
	v_mov_b64_e32 v[62:63], 0
	v_mov_b64_e32 v[64:65], 0
	v_mov_b64_e32 v[66:67], 0
	v_mov_b64_e32 v[68:69], 0
	v_mov_b64_e32 v[70:71], 0
	v_mov_b64_e32 v[72:73], 0
	v_mov_b64_e32 v[74:75], 0
	v_mov_b64_e32 v[76:77], 0
	v_mov_b64_e32 v[78:79], 0
	v_mov_b64_e32 v[80:81], 0
	v_mov_b64_e32 v[82:83], 0
	v_mov_b64_e32 v[84:85], 0
	v_mov_b64_e32 v[86:87], 0
	v_mov_b64_e32 v[88:89], 0
	v_mov_b64_e32 v[90:91], 0
	v_mov_b64_e32 v[92:93], 0
	v_mov_b64_e32 v[94:95], 0
	v_mov_b64_e32 v[96:97], 0
	v_mov_b64_e32 v[98:99], 0
	v_mov_b64_e32 v[100:101], 0
	v_mov_b64_e32 v[102:103], 0
	v_mov_b64_e32 v[104:105], 0
	v_mov_b64_e32 v[106:107], 0
	v_mov_b64_e32 v[108:109], 0
	v_mov_b64_e32 v[110:111], 0
	v_mov_b64_e32 v[112:113], 0
	v_mov_b64_e32 v[114:115], 0
	v_mov_b64_e32 v[116:117], 0
	v_mov_b64_e32 v[118:119], 0
	v_mov_b64_e32 v[120:121], 0
	v_mov_b64_e32 v[122:123], 0
	v_mov_b64_e32 v[124:125], 0
	v_mov_b64_e32 v[126:127], 0
	v_mov_b64_e32 v[128:129], 0

; template <class Epi>
; __device__ __forceinline__ void gemm_phase(LAS unsigned char* lds, const Gemm g, const StaticOrder& S, const Epi& E) {
;     ...
;         const bool has_next = S.next(ui + 1, nxt);
;         const char* nA = has_next ? (const char*)g.A + (size_t)nxt.pm * tstepA + (size_t)nxt.pn * ksb : cA; const char* nB = has_next ? (const char*)g.Bt + (size_t)nxt.pn * bstep : cB;
;     ...
; #pragma unroll
;         for (int a = 0; a < 2; ++a)
; #pragma unroll
;             for (int b = 0; b < 2; ++b)
; #pragma unroll
;                 for (int m = 0; m < 4; ++m)
; #pragma unroll
;                     for (int n = 0; n < 2; ++n) acc[a][b][m][n] = (f32x4){0.f, 0.f, 0.f, 0.f};
;         cur = nxt; cA = nA; cB = nB; ++ui;
.LBB0_700:
	s_ashr_i32 s21, s20, 31
	s_lshl_b64 s[22:23], s[20:21], 19
	s_add_u32 s22, s34, s22
	s_addc_u32 s23, s35, s23
	s_and_b64 s[24:25], s[12:13], exec
	s_cselect_b32 s21, s23, s29
	s_cselect_b32 s48, s22, s28
	s_ashr_i32 s19, s18, 31
	s_lshl_b64 s[24:25], s[18:19], 19
	s_add_u32 s24, s36, s24
	s_addc_u32 s25, s37, s25
	s_and_b64 s[30:31], s[12:13], exec
	s_cselect_b32 s19, s25, s27
	s_cselect_b32 s49, s24, s26
	s_add_u32 s50, s26, 0x100
	s_addc_u32 s51, s27, 0
	s_add_u32 s26, s28, 0x40080
	s_addc_u32 s27, s29, 0
	s_mov_b32 s52, -2
	v_mov_b64_e32 v[0:1], 0
	v_mov_b64_e32 v[2:3], 0
	v_mov_b64_e32 v[4:5], 0
	v_mov_b64_e32 v[6:7], 0
	v_mov_b64_e32 v[8:9], 0
	v_mov_b64_e32 v[10:11], 0
	v_mov_b64_e32 v[12:13], 0
	v_mov_b64_e32 v[14:15], 0
	v_mov_b64_e32 v[18:19], 0
	v_mov_b64_e32 v[20:21], 0
	v_mov_b64_e32 v[22:23], 0
	v_mov_b64_e32 v[24:25], 0
	v_mov_b64_e32 v[26:27], 0
	v_mov_b64_e32 v[28:29], 0
	v_mov_b64_e32 v[30:31], 0
	v_mov_b64_e32 v[32:33], 0
	v_mov_b64_e32 v[34:35], 0
	v_mov_b64_e32 v[36:37], 0
	v_mov_b64_e32 v[38:39], 0
	v_mov_b64_e32 v[40:41], 0
	v_mov_b64_e32 v[42:43], 0
	v_mov_b64_e32 v[44:45], 0
	v_mov_b64_e32 v[46:47], 0
	v_mov_b64_e32 v[48:49], 0
	v_mov_b64_e32 v[50:51], 0
	v_mov_b64_e32 v[52:53], 0
	v_mov_b64_e32 v[54:55], 0
	v_mov_b64_e32 v[56:57], 0
	v_mov_b64_e32 v[58:59], 0
	v_mov_b64_e32 v[60:61], 0
	v_mov_b64_e32 v[62:63], 0
	v_mov_b64_e32 v[64:65], 0
	v_mov_b64_e32 v[66:67], 0
	v_mov_b64_e32 v[68:69], 0
	v_mov_b64_e32 v[70:71], 0
	v_mov_b64_e32 v[72:73], 0
	v_mov_b64_e32 v[74:75], 0
	v_mov_b64_e32 v[76:77], 0
	v_mov_b64_e32 v[78:79], 0
	v_mov_b64_e32 v[80:81], 0
	v_mov_b64_e32 v[82:83], 0
	v_mov_b64_e32 v[84:85], 0
	v_mov_b64_e32 v[86:87], 0
	v_mov_b64_e32 v[88:89], 0
	v_mov_b64_e32 v[90:91], 0
	v_mov_b64_e32 v[92:93], 0
	v_mov_b64_e32 v[94:95], 0
	v_mov_b64_e32 v[96:97], 0
	v_mov_b64_e32 v[98:99], 0
	v_mov_b64_e32 v[100:101], 0
	v_mov_b64_e32 v[102:103], 0
	v_mov_b64_e32 v[104:105], 0
	v_mov_b64_e32 v[106:107], 0
	v_mov_b64_e32 v[108:109], 0
	v_mov_b64_e32 v[110:111], 0
	v_mov_b64_e32 v[112:113], 0
	v_mov_b64_e32 v[114:115], 0
	v_mov_b64_e32 v[116:117], 0
	v_mov_b64_e32 v[118:119], 0
	v_mov_b64_e32 v[120:121], 0
	v_mov_b64_e32 v[122:123], 0
	v_mov_b64_e32 v[124:125], 0
	v_mov_b64_e32 v[126:127], 0
	v_mov_b64_e32 v[128:129], 0
